# m21 + index unit prologue: the first pair's four key-fragment loads are no longer waited for before the staging barrier (vmcnt(4) instead of vmcnt(0); the step-A loop head has its own counted waits)
# speedup vs baseline: 1.0026x; 1.0026x over previous
.LBB0_1290:
	s_or_b64 exec, exec, s[0:1]
	s_and_b64 s[0:1], exec, s[58:59]
	v_readlane_b32 s0, v252, 62
	v_and_b32_e32 v167, 15, v36
	s_cselect_b32 s12, s0, s8
	v_ashrrev_i32_e32 v18, 4, v36
	v_or_b32_e32 v2, s92, v167
	v_readlane_b32 s0, v251, 48
	s_sub_i32 s77, s12, s3
	v_lshlrev_b32_e32 v188, 7, v2
	v_readlane_b32 s1, v251, 49
	v_lshlrev_b32_e32 v4, 3, v18
	v_ashrrev_i32_e32 v5, 31, v4
	v_lshl_add_u64 v[2:3], s[0:1], 0, v[188:189]
	s_cmp_gt_i32 s77, -1
	s_cselect_b64 s[78:79], -1, 0
	s_cmp_lt_i32 s77, 0
	v_lshl_add_u64 v[26:27], v[4:5], 1, v[2:3]
	s_cbranch_scc1 .LBB0_1292
	v_readlane_b32 s0, v252, 34
	v_readlane_b32 s1, v252, 35
	s_cmp_gt_u32 s77, 7
	s_nop 0
	v_lshl_add_u64 v[2:3], v[26:27], 0, s[0:1]
	v_readlane_b32 s0, v252, 31
	s_cselect_b32 s68, s0, s14
	s_lshl_b64 s[0:1], s[68:69], 7
	v_lshl_add_u64 v[10:11], v[26:27], 0, s[0:1]
	global_load_dwordx4 v[6:9], v[2:3], off
	s_nop 0
	global_load_dwordx4 v[2:5], v[2:3], off offset:64
	s_nop 0
	global_load_dwordx4 v[14:17], v[10:11], off
	s_nop 0
	global_load_dwordx4 v[10:13], v[10:11], off offset:64
	s_waitcnt vmcnt(4)
	s_branch .Lidx_pw0

.Lidx_pw0:
	v_cndmask_b32_e64 v19, 0, 1, s[78:79]
	v_cmp_ne_u32_e64 s[28:29], 1, v19
	s_andn2_b64 vcc, exec, s[78:79]
	v_lshlrev_b32_e32 v39, 4, v36
	v_lshlrev_b32_e32 v172, 2, v167
	v_lshl_add_u32 v40, v167, 13, 0
	v_lshl_add_u32 v41, v18, 2, s14
	s_waitcnt lgkmcnt(0)
	s_barrier
	s_cbranch_vccnz .LBB0_1383
	s_add_i32 s0, s77, 8
	s_lshr_b32 s1, s0, 29
	s_add_i32 s0, s0, s1
	s_ashr_i32 s13, s0, 3
	s_add_i32 s0, 0, 0x22200
	v_add_u32_e32 v173, s0, v39
	v_readlane_b32 s0, v251, 29
	s_add_i32 s14, s13, -2
	s_add_i32 s15, s13, -3
	v_add_u32_e32 v174, s0, v39
	s_max_i32 s0, s13, 2
	s_lshl_b32 s0, s0, 3
	s_add_i32 s0, s0, -8
	s_and_b32 s16, s0, -16
	v_or_b32_e32 v175, s24, v167
	s_add_i32 s16, s16, 16
	s_mov_b32 s17, 0
	v_mov_b64_e32 v[42:43], 0
	v_mov_b64_e32 v[44:45], 0
	v_mov_b64_e32 v[46:47], 0
	v_mov_b64_e32 v[48:49], 0
	v_mov_b64_e32 v[50:51], 0
	v_mov_b64_e32 v[52:53], 0
	v_mov_b64_e32 v[54:55], 0
	v_mov_b64_e32 v[56:57], 0
	v_mov_b64_e32 v[58:59], 0
	v_mov_b64_e32 v[60:61], 0
	v_mov_b64_e32 v[62:63], 0
	v_mov_b64_e32 v[64:65], 0
	v_mov_b64_e32 v[66:67], 0
	v_mov_b64_e32 v[68:69], 0
	v_mov_b64_e32 v[70:71], 0
	v_mov_b64_e32 v[72:73], 0
	v_mov_b64_e32 v[74:75], 0
	v_mov_b64_e32 v[76:77], 0
	v_mov_b64_e32 v[78:79], 0
	v_mov_b64_e32 v[80:81], 0
	v_mov_b64_e32 v[82:83], 0
	v_mov_b64_e32 v[84:85], 0
	v_mov_b64_e32 v[86:87], 0
	v_mov_b64_e32 v[88:89], 0
	v_mov_b64_e32 v[90:91], 0
	v_mov_b64_e32 v[92:93], 0
	v_mov_b64_e32 v[94:95], 0
	v_mov_b64_e32 v[96:97], 0
	v_mov_b64_e32 v[98:99], 0
	v_mov_b64_e32 v[100:101], 0
	v_mov_b64_e32 v[102:103], 0
	v_mov_b64_e32 v[104:105], 0
	v_mov_b64_e32 v[106:107], 0
	v_mov_b64_e32 v[108:109], 0
	v_mov_b64_e32 v[110:111], 0
	v_mov_b64_e32 v[112:113], 0
	v_mov_b64_e32 v[114:115], 0
	v_mov_b32_e32 v117, 0
	v_mov_b64_e32 v[118:119], 0
	v_mov_b64_e32 v[120:121], 0
	v_mov_b64_e32 v[122:123], 0
	v_mov_b64_e32 v[124:125], 0
	v_mov_b64_e32 v[126:127], 0
	v_mov_b64_e32 v[128:129], 0
	v_mov_b64_e32 v[130:131], 0
	v_mov_b64_e32 v[132:133], 0
	v_mov_b64_e32 v[134:135], 0
	v_mov_b64_e32 v[136:137], 0
	v_mov_b64_e32 v[138:139], 0
	v_mov_b64_e32 v[140:141], 0
	v_mov_b64_e32 v[142:143], 0
	v_mov_b64_e32 v[144:145], 0
	v_mov_b64_e32 v[146:147], 0
	v_mov_b64_e32 v[148:149], 0
	v_mov_b64_e32 v[150:151], 0
	v_mov_b64_e32 v[152:153], 0
	v_mov_b64_e32 v[154:155], 0
	v_mov_b64_e32 v[156:157], 0
	v_mov_b64_e32 v[158:159], 0
	v_mov_b64_e32 v[160:161], 0
	v_mov_b64_e32 v[162:163], 0
	v_mov_b64_e32 v[164:165], 0
	v_mov_b32_e32 v166, 0
	v_mov_b64_e32 v[168:169], 0
	v_mov_b64_e32 v[170:171], 0
	v_mov_b32_e32 v176, v41
	s_mov_b32 s18, 0
	s_mov_b32 s19, 0
	s_branch .LBB0_1296
